# attention phase: logical wave id remap (swap waves 4<->5, 6<->7) so each SIMD pair has one c==0 and one c==1 wave
# baseline (speedup 1.0000x reference)
.LBB0_226:
	v_readlane_b32 s100, v255, 2
	s_nop 3
	s_lshr_b32 s101, s100, 2
	s_and_b32 s101, s101, 1
	s_xor_b32 s100, s100, s101
	v_writelane_b32 v255, s100, 2
	s_lshl_b32 s101, s100, 6
	v_writelane_b32 v255, s101, 0
	v_writelane_b32 v255, s101, 1
	s_setprio 0
	v_writelane_b32 v255, s4, 28
	v_mov_b32_e32 v3, 0
	s_mov_b64 s[6:7], 0
	v_writelane_b32 v255, s5, 29
	v_mov_b32_e32 v0, 0
	v_mov_b32_e32 v1, v3
	s_barrier
	v_mbcnt_lo_u32_b32 v2, -1, 0
	v_mbcnt_hi_u32_b32 v2, -1, v2

.LBB0_268:
	v_readlane_b32 s100, v255, 2
	s_nop 3
	s_lshr_b32 s101, s100, 2
	s_and_b32 s101, s101, 1
	s_xor_b32 s100, s100, s101
	v_writelane_b32 v255, s100, 2
	s_lshl_b32 s101, s100, 6
	v_writelane_b32 v255, s101, 0
	v_writelane_b32 v255, s101, 1
	s_waitcnt vmcnt(0)
	v_readlane_b32 s70, v255, 28
	v_readlane_b32 s71, v255, 29
	s_and_b64 vcc, exec, s[70:71]
	s_barrier
	s_cbranch_vccnz .LBB0_276
	v_mbcnt_lo_u32_b32 v0, -1, 0
	v_mbcnt_hi_u32_b32 v0, -1, v0
	s_nop 0
	v_cmp_eq_u32_e32 vcc, 0, v0
	s_and_saveexec_b64 s[6:7], vcc
	s_cbranch_execz .LBB0_275
	s_mov_b64 s[8:9], exec
	buffer_wbl2 sc1
	s_waitcnt vmcnt(0)
	s_waitcnt vmcnt(0)
	v_mbcnt_lo_u32_b32 v0, s8, 0
	v_mbcnt_hi_u32_b32 v0, s9, v0
	v_cmp_eq_u32_e32 vcc, 0, v0
	s_and_saveexec_b64 s[10:11], vcc
	s_cbranch_execz .LBB0_272
	s_bcnt1_i32_b64 s0, s[8:9]
	v_mov_b32_e32 v0, 0
	v_mov_b32_e32 v1, s0
	global_atomic_add v0, v1, s[92:93]
